# v101: v99 with both wave groups split before P1 (waves 4-7 defer all sixteen PV MFMAs of a plain tile; waves 0-3 barrier before P1)
# baseline (speedup 1.0000x reference)
; #define ATT_PV(v_, p_) do { const bf16x8 pf_ = __builtin_bit_cast(bf16x8, (p_)); _Pragma("unroll") for (int d = 0; d < 4; ++d) { \
;         const bf16x8 vf_ = __builtin_shufflevector((v_)[2 * d], (v_)[2 * d + 1], 0, 1, 2, 3, 4, 5, 6, 7); O[d] = MFMA32(vf_, pf_, O[d]); } } while (0)
; template <bool ONLINE, int NO>
; __device__ __forceinline__ void softmax_tile(f32x16 (&s)[2], float& m, float& l, f32x16 (&O)[NO], u32x4 (&pk)[4]) {
;     ...
;     float ps = 0.f;
; #pragma unroll
;     for (int blk = 0; blk < 2; ++blk)
; #pragma unroll
;         for (int i = 0; i < 16; ++i) { const float p = __builtin_amdgcn_exp2f(ONLINE ? (s[blk][i] - mn) : s[blk][i]); ps += p; s[blk][i] = p; }
;     l += ps;
; #pragma unroll
;     for (int blk = 0; blk < 2; ++blk)
; #pragma unroll
;         for (int sh = 0; sh < 2; ++sh) { u32x4 pw;
;             pw.x = cvt_pk_bf16(s[blk][8 * sh], s[blk][8 * sh + 1]); pw.y = cvt_pk_bf16(s[blk][8 * sh + 2], s[blk][8 * sh + 3]);
;             pw.z = cvt_pk_bf16(s[blk][8 * sh + 4], s[blk][8 * sh + 5]); pw.w = cvt_pk_bf16(s[blk][8 * sh + 6], s[blk][8 * sh + 7]); pk[2 * blk + sh] = pw; }
; template <int MODE>
; __device__ __forceinline__ void attn_unit(const Params& P, LAS unsigned char* lds, const int b, const int h, const int qb) {
;     ...
;             softmax_tile<ONLINE, 4>(s, m1, l1, O, pk1);
;             if constexpr (MODE == 1) {
;                 v_issue<2>(vc, vaddr); v_wait<15>(va); ATT_PV(va, pk1[0]); v_issue<3>(vd, vaddr); v_wait<15>(vb); ATT_PV(vb, pk1[1]); v_wait<8>(vc); ATT_PV(vc, pk1[2]); v_wait<0>(vd); ATT_PV(vd, pk1[3]);
.LBB0_483:
	s_barrier
	s_cmpk_lt_u32 s58, 0x100
	s_cbranch_scc1 .LBB0_485
	s_cmp_eq_u32 s40, 0
	s_cbranch_scc1 .LmB_bar2
	s_add_i32 s41, s39, 0xffffff81
	s_cmp_le_i32 s41, s75
	s_cbranch_scc0 .LmB_bar2
	s_waitcnt lgkmcnt(8)
	v_mfma_f32_32x32x16_bf16 v[64:79], v[144:147], v[96:99], v[64:79]
	ds_read_b64_tr_b16 v[6:7], v0 offset:0x2000
	ds_read_b64_tr_b16 v[8:9], v0 offset:0x2100
	ds_read_b64_tr_b16 v[128:129], v0 offset:0x2200
	ds_read_b64_tr_b16 v[130:131], v0 offset:0x2300
	ds_read_b64_tr_b16 v[172:173], v0 offset:0x2400
	ds_read_b64_tr_b16 v[174:175], v0 offset:0x2500
	ds_read_b64_tr_b16 v[184:185], v0 offset:0x2600
	ds_read_b64_tr_b16 v[186:187], v0 offset:0x2700
	v_mfma_f32_32x32x16_bf16 v[48:63], v[140:143], v[96:99], v[48:63]
	v_exp_f32_e32 v247, v105
	v_exp_f32_e32 v248, v106
	v_exp_f32_e32 v249, v107
	v_mfma_f32_32x32x16_bf16 v[32:47], v[136:139], v[96:99], v[32:47]
	v_exp_f32_e32 v250, v108
	v_exp_f32_e32 v251, v109
	v_exp_f32_e32 v252, v110
	v_mfma_f32_32x32x16_bf16 v[16:31], v[132:135], v[96:99], v[16:31]
	v_exp_f32_e32 v253, v111
	v_add_f32_e32 v14, v15, v14
	v_cvt_pk_bf16_f32 v100, v246, v247
	v_cvt_pk_bf16_f32 v101, v248, v249
	v_cvt_pk_bf16_f32 v102, v250, v251
	v_add_f32_e32 v14, v240, v14
	v_cvt_pk_bf16_f32 v103, v252, v253
	v_add_f32_e32 v14, v241, v14
	s_waitcnt lgkmcnt(8)
	v_mfma_f32_32x32x16_bf16 v[64:79], v[168:171], v[100:103], v[64:79]
	ds_read_b64_tr_b16 v[144:145], v0 offset:0x3000
	ds_read_b64_tr_b16 v[146:147], v0 offset:0x3100
	ds_read_b64_tr_b16 v[140:141], v0 offset:0x3200
	ds_read_b64_tr_b16 v[142:143], v0 offset:0x3300
	ds_read_b64_tr_b16 v[136:137], v0 offset:0x3400
	ds_read_b64_tr_b16 v[138:139], v0 offset:0x3500
	ds_read_b64_tr_b16 v[132:133], v0 offset:0x3600
	ds_read_b64_tr_b16 v[134:135], v0 offset:0x3700
	v_mfma_f32_32x32x16_bf16 v[48:63], v[10:13], v[100:103], v[48:63]
	v_exp_f32_e32 v104, v80
	v_exp_f32_e32 v105, v81
	v_exp_f32_e32 v106, v82
	v_mfma_f32_32x32x16_bf16 v[32:47], v[180:183], v[100:103], v[32:47]
	v_exp_f32_e32 v107, v83
	v_exp_f32_e32 v108, v84
	v_exp_f32_e32 v109, v85
	v_mfma_f32_32x32x16_bf16 v[16:31], v[2:5], v[100:103], v[16:31]
	v_exp_f32_e32 v110, v86
	v_exp_f32_e32 v111, v87
	v_cvt_pk_bf16_f32 v80, v104, v105
	v_cvt_pk_bf16_f32 v81, v106, v107
	v_cvt_pk_bf16_f32 v82, v108, v109
	v_add_f32_e32 v14, v242, v14
	v_cvt_pk_bf16_f32 v83, v110, v111
	v_add_f32_e32 v14, v243, v14
	s_waitcnt lgkmcnt(8)
	v_mfma_f32_32x32x16_bf16 v[64:79], v[6:9], v[80:83], v[64:79]
	v_exp_f32_e32 v2, v88
	v_exp_f32_e32 v3, v89
	v_exp_f32_e32 v4, v90
	v_mfma_f32_32x32x16_bf16 v[48:63], v[128:131], v[80:83], v[48:63]
	v_exp_f32_e32 v5, v91
	v_exp_f32_e32 v10, v92
	v_exp_f32_e32 v11, v93
	v_mfma_f32_32x32x16_bf16 v[32:47], v[172:175], v[80:83], v[32:47]
	v_exp_f32_e32 v12, v94
	v_exp_f32_e32 v13, v95
	v_add_f32_e32 v14, v244, v14
	v_add_f32_e32 v14, v245, v14
	v_mfma_f32_32x32x16_bf16 v[16:31], v[184:187], v[80:83], v[16:31]
	v_cvt_pk_bf16_f32 v84, v2, v3
	v_cvt_pk_bf16_f32 v85, v4, v5
	v_cvt_pk_bf16_f32 v86, v10, v11
	v_add_f32_e32 v14, v246, v14
	v_cvt_pk_bf16_f32 v87, v12, v13
	v_add_f32_e32 v14, v247, v14
	v_add_f32_e32 v14, v248, v14
	s_waitcnt lgkmcnt(0)
	v_add_f32_e32 v14, v249, v14
	v_add_f32_e32 v14, v250, v14
	v_add_f32_e32 v14, v251, v14
	v_add_f32_e32 v14, v252, v14
	v_add_f32_e32 v14, v253, v14
	v_mfma_f32_32x32x16_bf16 v[64:79], v[144:147], v[84:87], v[64:79]
	v_add_f32_e32 v14, v104, v14
	v_add_f32_e32 v14, v105, v14
	v_add_f32_e32 v14, v106, v14
	v_add_f32_e32 v14, v107, v14
	v_add_f32_e32 v14, v108, v14
	v_add_f32_e32 v14, v109, v14
	v_mfma_f32_32x32x16_bf16 v[48:63], v[140:143], v[84:87], v[48:63]
	v_add_f32_e32 v14, v110, v14
	v_add_f32_e32 v14, v111, v14
	v_add_f32_e32 v14, v2, v14
	v_add_f32_e32 v14, v3, v14
	v_add_f32_e32 v14, v4, v14
	v_add_f32_e32 v14, v5, v14
	v_mfma_f32_32x32x16_bf16 v[32:47], v[136:139], v[84:87], v[32:47]
	v_add_f32_e32 v14, v10, v14
	v_add_f32_e32 v14, v11, v14
	v_add_f32_e32 v14, v12, v14
	v_add_f32_e32 v14, v13, v14
	v_add_f32_e32 v163, v163, v14
	v_mfma_f32_32x32x16_bf16 v[16:31], v[132:135], v[84:87], v[16:31]


; #define ATT_PV(v_, p_) do { const bf16x8 pf_ = __builtin_bit_cast(bf16x8, (p_)); _Pragma("unroll") for (int d = 0; d < 4; ++d) { \
;         const bf16x8 vf_ = __builtin_shufflevector((v_)[2 * d], (v_)[2 * d + 1], 0, 1, 2, 3, 4, 5, 6, 7); O[d] = MFMA32(vf_, pf_, O[d]); } } while (0)
; template <bool ONLINE, int NO>
; __device__ __forceinline__ void softmax_tile(f32x16 (&s)[2], float& m, float& l, f32x16 (&O)[NO], u32x4 (&pk)[4]) {
;     ...
;     float ps = 0.f;
; #pragma unroll
;     for (int blk = 0; blk < 2; ++blk)
; #pragma unroll
;         for (int i = 0; i < 16; ++i) { const float p = __builtin_amdgcn_exp2f(ONLINE ? (s[blk][i] - mn) : s[blk][i]); ps += p; s[blk][i] = p; }
;     l += ps;
; #pragma unroll
;     for (int blk = 0; blk < 2; ++blk)
; #pragma unroll
;         for (int sh = 0; sh < 2; ++sh) { u32x4 pw;
;             pw.x = cvt_pk_bf16(s[blk][8 * sh], s[blk][8 * sh + 1]); pw.y = cvt_pk_bf16(s[blk][8 * sh + 2], s[blk][8 * sh + 3]);
;             pw.z = cvt_pk_bf16(s[blk][8 * sh + 4], s[blk][8 * sh + 5]); pw.w = cvt_pk_bf16(s[blk][8 * sh + 6], s[blk][8 * sh + 7]); pk[2 * blk + sh] = pw; }
; template <int MODE>
; __device__ __forceinline__ void attn_unit(const Params& P, LAS unsigned char* lds, const int b, const int h, const int qb) {
;     ...
;             softmax_tile<ONLINE, 4>(s, m1, l1, O, pk1);
;             if constexpr (MODE == 1) {
;                 v_issue<2>(vc, vaddr); v_wait<15>(va); ATT_PV(va, pk1[0]); v_issue<3>(vd, vaddr); v_wait<15>(vb); ATT_PV(vb, pk1[1]); v_wait<8>(vc); ATT_PV(vc, pk1[2]); v_wait<0>(vd); ATT_PV(vd, pk1[3]);
.Lm1_fast:
	s_cmpk_lt_u32 s58, 0x100
	s_cbranch_scc0 .Lm1_fastB
	v_mfma_f32_32x32x16_bf16 v[96:111], v[2:5], v[112:115], 0
	v_mfma_f32_32x32x16_bf16 v[96:111], v[10:13], v[116:119], v[96:111]
	v_mfma_f32_32x32x16_bf16 v[96:111], v[168:171], v[120:123], v[96:111]
	v_mfma_f32_32x32x16_bf16 v[96:111], v[180:183], v[124:127], v[96:111]
	ds_read_b64_tr_b16 v[168:169], v0 offset:0x1000
	ds_read_b64_tr_b16 v[170:171], v0 offset:0x1100
	ds_read_b64_tr_b16 v[10:11], v0 offset:0x1200
	ds_read_b64_tr_b16 v[12:13], v0 offset:0x1300
	ds_read_b64_tr_b16 v[180:181], v0 offset:0x1400
	ds_read_b64_tr_b16 v[182:183], v0 offset:0x1500
	ds_read_b64_tr_b16 v[2:3], v0 offset:0x1600
	ds_read_b64_tr_b16 v[4:5], v0 offset:0x1700
	v_mfma_f32_32x32x16_bf16 v[80:95], v[6:9], v[112:115], 0
	s_nop 2
	v_exp_f32_e32 v14, v96
	v_exp_f32_e32 v15, v97
	v_mfma_f32_32x32x16_bf16 v[80:95], v[128:131], v[116:119], v[80:95]
	v_exp_f32_e32 v240, v98
	v_exp_f32_e32 v241, v99
	v_exp_f32_e32 v242, v100
	v_mfma_f32_32x32x16_bf16 v[80:95], v[172:175], v[120:123], v[80:95]
	v_exp_f32_e32 v243, v101
	v_exp_f32_e32 v244, v102
	v_exp_f32_e32 v245, v103
	v_mfma_f32_32x32x16_bf16 v[80:95], v[184:187], v[124:127], v[80:95]
	v_cvt_pk_bf16_f32 v96, v14, v15
	v_cvt_pk_bf16_f32 v97, v240, v241
	v_cvt_pk_bf16_f32 v98, v242, v243
	v_cvt_pk_bf16_f32 v99, v244, v245
	v_exp_f32_e32 v246, v104
	s_barrier
	s_waitcnt lgkmcnt(8)
	v_mfma_f32_32x32x16_bf16 v[64:79], v[144:147], v[96:99], v[64:79]
	ds_read_b64_tr_b16 v[6:7], v0 offset:0x2000
	ds_read_b64_tr_b16 v[8:9], v0 offset:0x2100
	ds_read_b64_tr_b16 v[128:129], v0 offset:0x2200
	ds_read_b64_tr_b16 v[130:131], v0 offset:0x2300
	ds_read_b64_tr_b16 v[172:173], v0 offset:0x2400
	ds_read_b64_tr_b16 v[174:175], v0 offset:0x2500
	ds_read_b64_tr_b16 v[184:185], v0 offset:0x2600
	ds_read_b64_tr_b16 v[186:187], v0 offset:0x2700
	v_mfma_f32_32x32x16_bf16 v[48:63], v[140:143], v[96:99], v[48:63]
	v_exp_f32_e32 v247, v105
	v_exp_f32_e32 v248, v106
	v_exp_f32_e32 v249, v107
	v_mfma_f32_32x32x16_bf16 v[32:47], v[136:139], v[96:99], v[32:47]
	v_exp_f32_e32 v250, v108
	v_exp_f32_e32 v251, v109
	v_exp_f32_e32 v252, v110
	v_mfma_f32_32x32x16_bf16 v[16:31], v[132:135], v[96:99], v[16:31]
	v_exp_f32_e32 v253, v111
	v_add_f32_e32 v14, v15, v14
	v_cvt_pk_bf16_f32 v100, v246, v247
	v_cvt_pk_bf16_f32 v101, v248, v249
	v_cvt_pk_bf16_f32 v102, v250, v251
	v_add_f32_e32 v14, v240, v14
	v_cvt_pk_bf16_f32 v103, v252, v253
	v_add_f32_e32 v14, v241, v14
	s_waitcnt lgkmcnt(8)
	v_mfma_f32_32x32x16_bf16 v[64:79], v[168:171], v[100:103], v[64:79]
	ds_read_b64_tr_b16 v[144:145], v0 offset:0x3000
	ds_read_b64_tr_b16 v[146:147], v0 offset:0x3100
	ds_read_b64_tr_b16 v[140:141], v0 offset:0x3200
	ds_read_b64_tr_b16 v[142:143], v0 offset:0x3300
	ds_read_b64_tr_b16 v[136:137], v0 offset:0x3400
	ds_read_b64_tr_b16 v[138:139], v0 offset:0x3500
	ds_read_b64_tr_b16 v[132:133], v0 offset:0x3600
	ds_read_b64_tr_b16 v[134:135], v0 offset:0x3700
	v_mfma_f32_32x32x16_bf16 v[48:63], v[10:13], v[100:103], v[48:63]
	v_exp_f32_e32 v104, v80
	v_exp_f32_e32 v105, v81
	v_exp_f32_e32 v106, v82
	v_mfma_f32_32x32x16_bf16 v[32:47], v[180:183], v[100:103], v[32:47]
	v_exp_f32_e32 v107, v83
	v_exp_f32_e32 v108, v84
	v_exp_f32_e32 v109, v85
	v_mfma_f32_32x32x16_bf16 v[16:31], v[2:5], v[100:103], v[16:31]
	v_exp_f32_e32 v110, v86
	v_exp_f32_e32 v111, v87
	v_cvt_pk_bf16_f32 v80, v104, v105
	v_cvt_pk_bf16_f32 v81, v106, v107
	v_cvt_pk_bf16_f32 v82, v108, v109
	v_add_f32_e32 v14, v242, v14
	v_cvt_pk_bf16_f32 v83, v110, v111
	v_add_f32_e32 v14, v243, v14
	s_waitcnt lgkmcnt(8)
	v_mfma_f32_32x32x16_bf16 v[64:79], v[6:9], v[80:83], v[64:79]
	v_exp_f32_e32 v2, v88
	v_exp_f32_e32 v3, v89
	v_exp_f32_e32 v4, v90
	v_mfma_f32_32x32x16_bf16 v[48:63], v[128:131], v[80:83], v[48:63]
	v_exp_f32_e32 v5, v91
	v_exp_f32_e32 v10, v92
	v_exp_f32_e32 v11, v93
	v_mfma_f32_32x32x16_bf16 v[32:47], v[172:175], v[80:83], v[32:47]
	v_exp_f32_e32 v12, v94
	v_exp_f32_e32 v13, v95
	v_add_f32_e32 v14, v244, v14
	v_add_f32_e32 v14, v245, v14
	v_mfma_f32_32x32x16_bf16 v[16:31], v[184:187], v[80:83], v[16:31]
	v_cvt_pk_bf16_f32 v84, v2, v3
	v_cvt_pk_bf16_f32 v85, v4, v5
	v_cvt_pk_bf16_f32 v86, v10, v11
	v_add_f32_e32 v14, v246, v14
	v_cvt_pk_bf16_f32 v87, v12, v13
	v_add_f32_e32 v14, v247, v14
	v_add_f32_e32 v14, v248, v14
	s_waitcnt lgkmcnt(0)
	v_add_f32_e32 v14, v249, v14
	v_add_f32_e32 v14, v250, v14
	v_add_f32_e32 v14, v251, v14
	v_add_f32_e32 v14, v252, v14
	v_add_f32_e32 v14, v253, v14
	s_add_i32 s41, s40, 3
	s_cmp_ge_u32 s41, s22
	s_cbranch_scc1 .Lm1f_nodma
	s_cmpk_gt_u32 s58, 0xff
	s_cbranch_scc1 .Lm1f_nodma
	v_mfma_f32_32x32x16_bf16 v[64:79], v[144:147], v[84:87], v[64:79]
	s_mov_b64 s[70:71], 0x1000
	s_add_i32 s41, s38, 0x18000
	s_and_b32 s41, s41, 0x18000
	s_add_i32 s41, s77, s41
	v_lshl_add_u64 v[240:241], v[152:153], 0, s[68:69]
	v_lshl_add_u64 v[242:243], v[240:241], 0, s[42:43]
	s_mov_b32 m0, s41
	v_lshl_add_u64 v[240:241], v[240:241], 0, s[44:45]
	global_load_lds_dwordx4 v[242:243], off
	v_mfma_f32_32x32x16_bf16 v[48:63], v[140:143], v[84:87], v[48:63]
	s_add_i32 m0, s41, 0x1000
	v_lshl_add_u64 v[242:243], v[242:243], 0, s[70:71]
	global_load_lds_dwordx4 v[242:243], off
	s_add_i32 m0, s41, 0x2000
	v_lshl_add_u64 v[242:243], v[240:241], 0, s[70:71]
	global_load_lds_dwordx4 v[240:241], off
	s_add_i32 m0, s41, 0x3000
	v_lshl_add_u64 v[240:241], v[154:155], 0, s[68:69]
	global_load_lds_dwordx4 v[242:243], off
	v_add_f32_e32 v14, v104, v14
	v_add_f32_e32 v14, v105, v14
	v_add_f32_e32 v14, v106, v14
	v_add_f32_e32 v14, v107, v14
	v_mfma_f32_32x32x16_bf16 v[32:47], v[136:139], v[84:87], v[32:47]
	v_lshl_add_u64 v[242:243], v[240:241], 0, s[48:49]
	s_add_i32 m0, s41, 0x4000
	v_lshl_add_u64 v[240:241], v[240:241], 0, s[50:51]
	global_load_lds_dwordx4 v[242:243], off
	s_add_i32 m0, s41, 0x5000
	v_lshl_add_u64 v[242:243], v[242:243], 0, s[70:71]
	global_load_lds_dwordx4 v[242:243], off
	v_add_f32_e32 v14, v108, v14
	v_add_f32_e32 v14, v109, v14
	v_add_f32_e32 v14, v110, v14
	v_add_f32_e32 v14, v111, v14
	v_add_f32_e32 v14, v2, v14
	v_add_f32_e32 v14, v3, v14
	v_mfma_f32_32x32x16_bf16 v[16:31], v[132:135], v[84:87], v[16:31]
	s_add_i32 m0, s41, 0x6000
	v_lshl_add_u64 v[242:243], v[240:241], 0, s[70:71]
	global_load_lds_dwordx4 v[240:241], off
	s_add_i32 m0, s41, 0x7000
	s_nop 0
	global_load_lds_dwordx4 v[242:243], off
	v_add_f32_e32 v14, v4, v14
	v_add_f32_e32 v14, v5, v14
	v_add_f32_e32 v14, v10, v14
	v_add_f32_e32 v14, v11, v14
	v_add_f32_e32 v14, v12, v14
	v_add_f32_e32 v14, v13, v14
	v_add_f32_e32 v163, v163, v14
	s_branch .LBB0_474

; #define ATT_PV(v_, p_) do { const bf16x8 pf_ = __builtin_bit_cast(bf16x8, (p_)); _Pragma("unroll") for (int d = 0; d < 4; ++d) { \
;         const bf16x8 vf_ = __builtin_shufflevector((v_)[2 * d], (v_)[2 * d + 1], 0, 1, 2, 3, 4, 5, 6, 7); O[d] = MFMA32(vf_, pf_, O[d]); } } while (0)
; template <bool ONLINE, int NO>
; __device__ __forceinline__ void softmax_tile(f32x16 (&s)[2], float& m, float& l, f32x16 (&O)[NO], u32x4 (&pk)[4]) {
;     ...
;     float ps = 0.f;
; #pragma unroll
;     for (int blk = 0; blk < 2; ++blk)
; #pragma unroll
;         for (int i = 0; i < 16; ++i) { const float p = __builtin_amdgcn_exp2f(ONLINE ? (s[blk][i] - mn) : s[blk][i]); ps += p; s[blk][i] = p; }
;     l += ps;
; #pragma unroll
;     for (int blk = 0; blk < 2; ++blk)
; #pragma unroll
;         for (int sh = 0; sh < 2; ++sh) { u32x4 pw;
;             pw.x = cvt_pk_bf16(s[blk][8 * sh], s[blk][8 * sh + 1]); pw.y = cvt_pk_bf16(s[blk][8 * sh + 2], s[blk][8 * sh + 3]);
;             pw.z = cvt_pk_bf16(s[blk][8 * sh + 4], s[blk][8 * sh + 5]); pw.w = cvt_pk_bf16(s[blk][8 * sh + 6], s[blk][8 * sh + 7]); pk[2 * blk + sh] = pw; }
; template <int MODE>
; __device__ __forceinline__ void attn_unit(const Params& P, LAS unsigned char* lds, const int b, const int h, const int qb) {
;     ...
;             softmax_tile<ONLINE, 4>(s, m1, l1, O, pk1);
;             if constexpr (MODE == 1) {
;                 v_issue<2>(vc, vaddr); v_wait<15>(va); ATT_PV(va, pk1[0]); v_issue<3>(vd, vaddr); v_wait<15>(vb); ATT_PV(vb, pk1[1]); v_wait<8>(vc); ATT_PV(vc, pk1[2]); v_wait<0>(vd); ATT_PV(vd, pk1[3]);
.Lm1_fastB:
	v_mfma_f32_32x32x16_bf16 v[96:111], v[2:5], v[112:115], 0
	v_mfma_f32_32x32x16_bf16 v[96:111], v[10:13], v[116:119], v[96:111]
	v_mfma_f32_32x32x16_bf16 v[96:111], v[168:171], v[120:123], v[96:111]
	v_mfma_f32_32x32x16_bf16 v[96:111], v[180:183], v[124:127], v[96:111]
	ds_read_b64_tr_b16 v[168:169], v0 offset:0x1000
	ds_read_b64_tr_b16 v[170:171], v0 offset:0x1100
	ds_read_b64_tr_b16 v[10:11], v0 offset:0x1200
	ds_read_b64_tr_b16 v[12:13], v0 offset:0x1300
	ds_read_b64_tr_b16 v[180:181], v0 offset:0x1400
	ds_read_b64_tr_b16 v[182:183], v0 offset:0x1500
	ds_read_b64_tr_b16 v[2:3], v0 offset:0x1600
	ds_read_b64_tr_b16 v[4:5], v0 offset:0x1700
	v_mfma_f32_32x32x16_bf16 v[80:95], v[6:9], v[112:115], 0
	s_nop 2
	v_exp_f32_e32 v14, v96
	v_exp_f32_e32 v15, v97
	v_mfma_f32_32x32x16_bf16 v[80:95], v[128:131], v[116:119], v[80:95]
	v_exp_f32_e32 v240, v98
	v_exp_f32_e32 v241, v99
	v_exp_f32_e32 v242, v100
	v_mfma_f32_32x32x16_bf16 v[80:95], v[172:175], v[120:123], v[80:95]
	v_exp_f32_e32 v243, v101
	v_exp_f32_e32 v244, v102
	v_exp_f32_e32 v245, v103
	v_mfma_f32_32x32x16_bf16 v[80:95], v[184:187], v[124:127], v[80:95]
	v_cvt_pk_bf16_f32 v96, v14, v15
	v_cvt_pk_bf16_f32 v97, v240, v241
	v_cvt_pk_bf16_f32 v98, v242, v243
	v_cvt_pk_bf16_f32 v99, v244, v245
	v_exp_f32_e32 v246, v104
	s_branch .LBB0_474
